# swiglu GEMM: row-scale loads for the epilogue issued in the last K-iteration (counted wait), no load/drain at the epilogue start
# baseline (speedup 1.0000x reference)
.LBB0_500:
	s_add_u32 s44, s42, 0x100
	s_addc_u32 s45, s43, 0
	s_cmp_eq_u32 s63, 12
	s_cselect_b32 s50, s26, s44
	s_cselect_b32 s51, s5, s45
	s_cselect_b32 s48, s27, s28
	s_cselect_b32 s49, s23, s29
	s_add_i32 s64, 0, 0x10000
	s_add_u32 s46, s42, 0x80
	s_addc_u32 s47, s43, 0
	s_add_u32 s42, s42, 0x40080
	s_addc_u32 s43, s43, 0
	s_mov_b32 m0, s60
	s_nop 0
	global_load_lds_dwordx4 v144, s[46:47]
	s_mov_b32 m0, s61
	s_nop 0
	global_load_lds_dwordx4 v140, s[46:47]
	v_add_u32_e32 v138, s64, v3
	s_add_i32 s65, 0, 0x14000
	ds_read_b128 v[146:149], v138
	ds_read_b128 v[150:153], v138 offset:1024
	ds_read_b128 v[154:157], v138 offset:2048
	ds_read_b128 v[158:161], v138 offset:3072
	v_add_u32_e32 v138, s65, v3
	ds_read_b128 v[162:165], v138
	ds_read_b128 v[166:169], v138 offset:1024
	ds_read_b128 v[170:173], v138 offset:2048
	ds_read_b128 v[186:189], v138 offset:3072
	s_add_i32 m0, s56, 0xc000
	s_nop 0
	global_load_lds_dwordx4 v144, s[42:43]
	s_add_i32 m0, s56, 0xe000
	s_nop 0
	global_load_lds_dwordx4 v140, s[42:43]
	ds_read_b128 v[190:193], v132
	ds_read_b128 v[194:197], v132 offset:1024
	ds_read_b128 v[198:201], v132 offset:2048
	ds_read_b128 v[202:205], v132 offset:3072
	ds_read_b128 v[206:209], v132 offset:4096
	ds_read_b128 v[210:213], v132 offset:5120
	ds_read_b128 v[214:217], v132 offset:6144
	ds_read_b128 v[218:221], v132 offset:7168
	s_waitcnt vmcnt(8)
	s_waitcnt lgkmcnt(8)
	s_barrier
	s_setprio 1
	s_waitcnt lgkmcnt(0)
	v_mfma_f32_16x16x32_bf16 v[128:131], v[146:149], v[190:193], v[128:131]
	v_mfma_f32_16x16x32_bf16 v[124:127], v[154:157], v[190:193], v[124:127]
	v_mfma_f32_16x16x32_bf16 v[112:115], v[146:149], v[198:201], v[112:115]
	v_mfma_f32_16x16x32_bf16 v[108:111], v[154:157], v[198:201], v[108:111]
	v_mfma_f32_16x16x32_bf16 v[96:99], v[146:149], v[206:209], v[96:99]
	v_mfma_f32_16x16x32_bf16 v[92:95], v[154:157], v[206:209], v[92:95]
	v_mfma_f32_16x16x32_bf16 v[80:83], v[146:149], v[214:217], v[80:83]
	v_mfma_f32_16x16x32_bf16 v[76:79], v[154:157], v[214:217], v[76:79]
	v_mfma_f32_16x16x32_bf16 v[128:131], v[150:153], v[194:197], v[128:131]
	v_mfma_f32_16x16x32_bf16 v[124:127], v[158:161], v[194:197], v[124:127]
	v_mfma_f32_16x16x32_bf16 v[112:115], v[150:153], v[202:205], v[112:115]
	v_mfma_f32_16x16x32_bf16 v[108:111], v[158:161], v[202:205], v[108:111]
	v_mfma_f32_16x16x32_bf16 v[96:99], v[150:153], v[210:213], v[96:99]
	v_mfma_f32_16x16x32_bf16 v[92:95], v[158:161], v[210:213], v[92:95]
	v_mfma_f32_16x16x32_bf16 v[80:83], v[150:153], v[218:221], v[80:83]
	v_mfma_f32_16x16x32_bf16 v[76:79], v[158:161], v[218:221], v[76:79]
	s_setprio 0
	s_setprio 1
	v_mfma_f32_16x16x32_bf16 v[120:123], v[162:165], v[190:193], v[120:123]
	v_mfma_f32_16x16x32_bf16 v[116:119], v[170:173], v[190:193], v[116:119]
	v_mfma_f32_16x16x32_bf16 v[104:107], v[162:165], v[198:201], v[104:107]
	v_mfma_f32_16x16x32_bf16 v[100:103], v[170:173], v[198:201], v[100:103]
	v_mfma_f32_16x16x32_bf16 v[88:91], v[162:165], v[206:209], v[88:91]
	v_mfma_f32_16x16x32_bf16 v[84:87], v[170:173], v[206:209], v[84:87]
	v_mfma_f32_16x16x32_bf16 v[72:75], v[162:165], v[214:217], v[72:75]
	v_mfma_f32_16x16x32_bf16 v[68:71], v[170:173], v[214:217], v[68:71]
	v_mfma_f32_16x16x32_bf16 v[120:123], v[166:169], v[194:197], v[120:123]
	v_mfma_f32_16x16x32_bf16 v[116:119], v[186:189], v[194:197], v[116:119]
	v_mfma_f32_16x16x32_bf16 v[104:107], v[166:169], v[202:205], v[104:107]
	v_mfma_f32_16x16x32_bf16 v[100:103], v[186:189], v[202:205], v[100:103]
	v_mfma_f32_16x16x32_bf16 v[88:91], v[166:169], v[210:213], v[88:91]
	v_mfma_f32_16x16x32_bf16 v[84:87], v[186:189], v[210:213], v[84:87]
	v_mfma_f32_16x16x32_bf16 v[72:75], v[166:169], v[218:221], v[72:75]
	v_mfma_f32_16x16x32_bf16 v[68:71], v[186:189], v[218:221], v[68:71]
	s_setprio 0
	s_barrier
	s_add_i32 s42, s64, s69
	s_mov_b32 m0, s42
	s_nop 0
	global_load_lds_dwordx4 v142, s[48:49]
	s_add_i32 m0, s42, 0x2000
	s_add_u32 s42, s48, 0x40000
	s_addc_u32 s43, s49, 0
	s_add_i32 s64, s65, s69
	global_load_lds_dwordx4 v0, s[48:49]
	s_mov_b32 m0, s64
	s_nop 0
	global_load_lds_dwordx4 v142, s[42:43]
	s_add_i32 m0, s64, 0x2000
	s_nop 0
	global_load_lds_dwordx4 v0, s[42:43]
	ds_read_b128 v[190:193], v132 offset:16384
	ds_read_b128 v[194:197], v132 offset:17408
	ds_read_b128 v[198:201], v132 offset:18432
	ds_read_b128 v[202:205], v132 offset:19456
	ds_read_b128 v[206:209], v132 offset:20480
	ds_read_b128 v[210:213], v132 offset:21504
	ds_read_b128 v[214:217], v132 offset:22528
	ds_read_b128 v[218:221], v132 offset:23552
	s_waitcnt vmcnt(6)
	s_waitcnt lgkmcnt(0)
	s_barrier
	s_setprio 1
	s_waitcnt lgkmcnt(0)
	v_mfma_f32_16x16x32_bf16 v[64:67], v[146:149], v[190:193], v[64:67]
	v_mfma_f32_16x16x32_bf16 v[60:63], v[154:157], v[190:193], v[60:63]
	v_mfma_f32_16x16x32_bf16 v[48:51], v[146:149], v[198:201], v[48:51]
	v_mfma_f32_16x16x32_bf16 v[44:47], v[154:157], v[198:201], v[44:47]
	v_mfma_f32_16x16x32_bf16 v[32:35], v[146:149], v[206:209], v[32:35]
	v_mfma_f32_16x16x32_bf16 v[28:31], v[154:157], v[206:209], v[28:31]
	v_mfma_f32_16x16x32_bf16 v[16:19], v[146:149], v[214:217], v[16:19]
	v_mfma_f32_16x16x32_bf16 v[12:15], v[154:157], v[214:217], v[12:15]
	v_mfma_f32_16x16x32_bf16 v[64:67], v[150:153], v[194:197], v[64:67]
	v_mfma_f32_16x16x32_bf16 v[60:63], v[158:161], v[194:197], v[60:63]
	v_mfma_f32_16x16x32_bf16 v[48:51], v[150:153], v[202:205], v[48:51]
	v_mfma_f32_16x16x32_bf16 v[44:47], v[158:161], v[202:205], v[44:47]
	v_mfma_f32_16x16x32_bf16 v[32:35], v[150:153], v[210:213], v[32:35]
	v_mfma_f32_16x16x32_bf16 v[28:31], v[158:161], v[210:213], v[28:31]
	v_mfma_f32_16x16x32_bf16 v[16:19], v[150:153], v[218:221], v[16:19]
	v_mfma_f32_16x16x32_bf16 v[12:15], v[158:161], v[218:221], v[12:15]
	s_setprio 0
	s_setprio 1
	v_mfma_f32_16x16x32_bf16 v[56:59], v[162:165], v[190:193], v[56:59]
	v_mfma_f32_16x16x32_bf16 v[52:55], v[170:173], v[190:193], v[52:55]
	v_mfma_f32_16x16x32_bf16 v[40:43], v[162:165], v[198:201], v[40:43]
	v_mfma_f32_16x16x32_bf16 v[36:39], v[170:173], v[198:201], v[36:39]
	v_mfma_f32_16x16x32_bf16 v[24:27], v[162:165], v[206:209], v[24:27]
	v_mfma_f32_16x16x32_bf16 v[20:23], v[170:173], v[206:209], v[20:23]
	v_mfma_f32_16x16x32_bf16 v[8:11], v[162:165], v[214:217], v[8:11]
	v_mfma_f32_16x16x32_bf16 v[4:7], v[170:173], v[214:217], v[4:7]
	v_mfma_f32_16x16x32_bf16 v[56:59], v[166:169], v[194:197], v[56:59]
	v_mfma_f32_16x16x32_bf16 v[52:55], v[186:189], v[194:197], v[52:55]
	v_mfma_f32_16x16x32_bf16 v[40:43], v[166:169], v[202:205], v[40:43]
	v_mfma_f32_16x16x32_bf16 v[36:39], v[186:189], v[202:205], v[36:39]
	v_mfma_f32_16x16x32_bf16 v[24:27], v[166:169], v[210:213], v[24:27]
	v_mfma_f32_16x16x32_bf16 v[20:23], v[186:189], v[210:213], v[20:23]
	v_mfma_f32_16x16x32_bf16 v[8:11], v[166:169], v[218:221], v[8:11]
	v_mfma_f32_16x16x32_bf16 v[4:7], v[186:189], v[218:221], v[4:7]
	s_setprio 0
	s_barrier
	s_add_i32 s64, 0, 0x18000
	s_add_u32 s42, s50, 0x40000
	s_addc_u32 s43, s51, 0
	s_mov_b32 m0, s56
	s_nop 0
	global_load_lds_dwordx4 v144, s[50:51]
	s_mov_b32 m0, s57
	s_nop 0
	global_load_lds_dwordx4 v140, s[50:51]
	v_add_u32_e32 v138, s64, v3
	s_add_i32 s65, 0, 0x1c000
	ds_read_b128 v[146:149], v138
	ds_read_b128 v[150:153], v138 offset:1024
	ds_read_b128 v[154:157], v138 offset:2048
	ds_read_b128 v[158:161], v138 offset:3072
	v_add_u32_e32 v138, s65, v3
	ds_read_b128 v[162:165], v138
	ds_read_b128 v[166:169], v138 offset:1024
	ds_read_b128 v[170:173], v138 offset:2048
	ds_read_b128 v[186:189], v138 offset:3072
	s_mov_b32 m0, s58
	s_nop 0
	global_load_lds_dwordx4 v144, s[42:43]
	s_mov_b32 m0, s59
	s_nop 0
	global_load_lds_dwordx4 v140, s[42:43]
	s_cmp_eq_u32 s63, 12
	s_cbranch_scc0 .Lgu_nors
	s_lshl_b32 s46, s9, 8
	s_add_i32 s46, s46, s70
	v_mov_b32_e32 v223, 0
	v_and_or_b32 v222, v174, 15, s46
	v_lshl_add_u64 v[222:223], v[222:223], 2, s[2:3]
	global_load_dword v224, v[222:223], off
	global_load_dword v226, v[222:223], off offset:64
	global_load_dword v228, v[222:223], off offset:128
	global_load_dword v230, v[222:223], off offset:192
	global_load_dword v232, v[222:223], off offset:512
	global_load_dword v234, v[222:223], off offset:576
	global_load_dword v236, v[222:223], off offset:640
	global_load_dword v238, v[222:223], off offset:704
.Lgu_nors:
	ds_read_b128 v[190:193], v132 offset:32768
	ds_read_b128 v[194:197], v132 offset:33792
	ds_read_b128 v[198:201], v132 offset:34816
	ds_read_b128 v[202:205], v132 offset:35840
	ds_read_b128 v[206:209], v132 offset:36864
	ds_read_b128 v[210:213], v132 offset:37888
	ds_read_b128 v[214:217], v132 offset:38912
	ds_read_b128 v[218:221], v132 offset:39936
	s_cmp_eq_u32 s63, 12
	s_cbranch_scc1 .Lgu_wc_last
	s_waitcnt vmcnt(8)
	s_branch .Lgu_wc_done
.Lgu_wc_last:
	s_waitcnt vmcnt(16)
.Lgu_wc_done:
	s_waitcnt lgkmcnt(8)
	s_barrier
	s_setprio 1
	s_waitcnt lgkmcnt(0)
	v_mfma_f32_16x16x32_bf16 v[128:131], v[146:149], v[190:193], v[128:131]
	v_mfma_f32_16x16x32_bf16 v[124:127], v[154:157], v[190:193], v[124:127]
	v_mfma_f32_16x16x32_bf16 v[112:115], v[146:149], v[198:201], v[112:115]
	v_mfma_f32_16x16x32_bf16 v[108:111], v[154:157], v[198:201], v[108:111]
	v_mfma_f32_16x16x32_bf16 v[96:99], v[146:149], v[206:209], v[96:99]
	v_mfma_f32_16x16x32_bf16 v[92:95], v[154:157], v[206:209], v[92:95]
	v_mfma_f32_16x16x32_bf16 v[80:83], v[146:149], v[214:217], v[80:83]
	v_mfma_f32_16x16x32_bf16 v[76:79], v[154:157], v[214:217], v[76:79]
	v_mfma_f32_16x16x32_bf16 v[128:131], v[150:153], v[194:197], v[128:131]
	v_mfma_f32_16x16x32_bf16 v[124:127], v[158:161], v[194:197], v[124:127]
	v_mfma_f32_16x16x32_bf16 v[112:115], v[150:153], v[202:205], v[112:115]
	v_mfma_f32_16x16x32_bf16 v[108:111], v[158:161], v[202:205], v[108:111]
	v_mfma_f32_16x16x32_bf16 v[96:99], v[150:153], v[210:213], v[96:99]
	v_mfma_f32_16x16x32_bf16 v[92:95], v[158:161], v[210:213], v[92:95]
	v_mfma_f32_16x16x32_bf16 v[80:83], v[150:153], v[218:221], v[80:83]
	v_mfma_f32_16x16x32_bf16 v[76:79], v[158:161], v[218:221], v[76:79]
	s_setprio 0
	s_setprio 1
	v_mfma_f32_16x16x32_bf16 v[120:123], v[162:165], v[190:193], v[120:123]
	v_mfma_f32_16x16x32_bf16 v[116:119], v[170:173], v[190:193], v[116:119]
	v_mfma_f32_16x16x32_bf16 v[104:107], v[162:165], v[198:201], v[104:107]
	v_mfma_f32_16x16x32_bf16 v[100:103], v[170:173], v[198:201], v[100:103]
	v_mfma_f32_16x16x32_bf16 v[88:91], v[162:165], v[206:209], v[88:91]
	v_mfma_f32_16x16x32_bf16 v[84:87], v[170:173], v[206:209], v[84:87]
	v_mfma_f32_16x16x32_bf16 v[72:75], v[162:165], v[214:217], v[72:75]
	v_mfma_f32_16x16x32_bf16 v[68:71], v[170:173], v[214:217], v[68:71]
	v_mfma_f32_16x16x32_bf16 v[120:123], v[166:169], v[194:197], v[120:123]
	v_mfma_f32_16x16x32_bf16 v[116:119], v[186:189], v[194:197], v[116:119]
	v_mfma_f32_16x16x32_bf16 v[104:107], v[166:169], v[202:205], v[104:107]
	v_mfma_f32_16x16x32_bf16 v[100:103], v[186:189], v[202:205], v[100:103]
	v_mfma_f32_16x16x32_bf16 v[88:91], v[166:169], v[210:213], v[88:91]
	v_mfma_f32_16x16x32_bf16 v[84:87], v[186:189], v[210:213], v[84:87]
	v_mfma_f32_16x16x32_bf16 v[72:75], v[166:169], v[218:221], v[72:75]
	v_mfma_f32_16x16x32_bf16 v[68:71], v[186:189], v[218:221], v[68:71]
	s_setprio 0
	s_barrier
	s_add_u32 s42, s48, 0x80
	s_addc_u32 s43, s49, 0
	s_add_i32 s50, s64, s69
	s_mov_b32 m0, s50
	s_nop 0
	global_load_lds_dwordx4 v142, s[42:43]
	s_add_i32 m0, s50, 0x2000
	s_nop 0
	global_load_lds_dwordx4 v0, s[42:43]
	s_add_u32 s42, s48, 0x40080
	s_addc_u32 s43, s49, 0
	s_add_i32 s48, s65, s69
	s_mov_b32 m0, s48
	s_nop 0
	global_load_lds_dwordx4 v142, s[42:43]
	s_add_i32 m0, s48, 0x2000
	s_nop 0
	global_load_lds_dwordx4 v0, s[42:43]
	ds_read_b128 v[190:193], v132 offset:49152
	ds_read_b128 v[194:197], v132 offset:50176
	ds_read_b128 v[198:201], v132 offset:51200
	ds_read_b128 v[202:205], v132 offset:52224
	ds_read_b128 v[206:209], v132 offset:53248
	ds_read_b128 v[210:213], v132 offset:54272
	ds_read_b128 v[214:217], v132 offset:55296
	ds_read_b128 v[218:221], v132 offset:56320
	s_waitcnt vmcnt(6)
	s_waitcnt lgkmcnt(0)
	s_barrier
	s_setprio 1
	s_waitcnt lgkmcnt(0)
	v_mfma_f32_16x16x32_bf16 v[64:67], v[146:149], v[190:193], v[64:67]
	v_mfma_f32_16x16x32_bf16 v[60:63], v[154:157], v[190:193], v[60:63]
	v_mfma_f32_16x16x32_bf16 v[48:51], v[146:149], v[198:201], v[48:51]
	v_mfma_f32_16x16x32_bf16 v[44:47], v[154:157], v[198:201], v[44:47]
	v_mfma_f32_16x16x32_bf16 v[32:35], v[146:149], v[206:209], v[32:35]
	v_mfma_f32_16x16x32_bf16 v[28:31], v[154:157], v[206:209], v[28:31]
	v_mfma_f32_16x16x32_bf16 v[16:19], v[146:149], v[214:217], v[16:19]
	v_mfma_f32_16x16x32_bf16 v[12:15], v[154:157], v[214:217], v[12:15]
	v_mfma_f32_16x16x32_bf16 v[64:67], v[150:153], v[194:197], v[64:67]
	v_mfma_f32_16x16x32_bf16 v[60:63], v[158:161], v[194:197], v[60:63]
	v_mfma_f32_16x16x32_bf16 v[48:51], v[150:153], v[202:205], v[48:51]
	v_mfma_f32_16x16x32_bf16 v[44:47], v[158:161], v[202:205], v[44:47]
	v_mfma_f32_16x16x32_bf16 v[32:35], v[150:153], v[210:213], v[32:35]
	v_mfma_f32_16x16x32_bf16 v[28:31], v[158:161], v[210:213], v[28:31]
	v_mfma_f32_16x16x32_bf16 v[16:19], v[150:153], v[218:221], v[16:19]
	v_mfma_f32_16x16x32_bf16 v[12:15], v[158:161], v[218:221], v[12:15]
	s_setprio 0
	s_setprio 1
	v_mfma_f32_16x16x32_bf16 v[56:59], v[162:165], v[190:193], v[56:59]
	v_mfma_f32_16x16x32_bf16 v[52:55], v[170:173], v[190:193], v[52:55]
	v_mfma_f32_16x16x32_bf16 v[40:43], v[162:165], v[198:201], v[40:43]
	v_mfma_f32_16x16x32_bf16 v[36:39], v[170:173], v[198:201], v[36:39]
	v_mfma_f32_16x16x32_bf16 v[24:27], v[162:165], v[206:209], v[24:27]
	v_mfma_f32_16x16x32_bf16 v[20:23], v[170:173], v[206:209], v[20:23]
	v_mfma_f32_16x16x32_bf16 v[8:11], v[162:165], v[214:217], v[8:11]
	v_mfma_f32_16x16x32_bf16 v[4:7], v[170:173], v[214:217], v[4:7]
	v_mfma_f32_16x16x32_bf16 v[56:59], v[166:169], v[194:197], v[56:59]
	v_mfma_f32_16x16x32_bf16 v[52:55], v[186:189], v[194:197], v[52:55]
	v_mfma_f32_16x16x32_bf16 v[40:43], v[166:169], v[202:205], v[40:43]
	v_mfma_f32_16x16x32_bf16 v[36:39], v[186:189], v[202:205], v[36:39]
	v_mfma_f32_16x16x32_bf16 v[24:27], v[166:169], v[210:213], v[24:27]
	v_mfma_f32_16x16x32_bf16 v[20:23], v[186:189], v[210:213], v[20:23]
	v_mfma_f32_16x16x32_bf16 v[8:11], v[166:169], v[218:221], v[8:11]
	v_mfma_f32_16x16x32_bf16 v[4:7], v[186:189], v[218:221], v[4:7]
	s_setprio 0
	s_barrier
	s_add_i32 s63, s63, 2
	s_add_u32 s28, s28, 0x100
	s_addc_u32 s29, s29, 0
	s_cmp_gt_u32 s63, 13
	s_mov_b64 s[42:43], s[44:45]
	s_cbranch_scc0 .LBB0_500
	s_and_b64 vcc, exec, s[14:15]
	s_cbranch_vccz .LBB0_503
	s_barrier
.LBB0_503:
	v_mov_b32_e32 v139, v174
	s_lshl_b32 s5, s9, 8
	s_add_i32 s5, s5, s70
	v_and_or_b32 v138, v139, 15, s5
	s_lshl_b32 s5, s8, 7
	v_ashrrev_i32_e32 v139, 1, v139
	s_or_b32 s5, s5, s71
	v_and_b32_e32 v139, -8, v139
	v_add_u32_e32 v148, s5, v139
	v_ashrrev_i32_e32 v149, 31, v148
	v_mov_b64_e32 v[146:147], s[0:1]
	v_ashrrev_i32_e32 v139, 31, v138
	v_mad_i64_i32 v[150:151], s[8:9], v138, s73, v[146:147]
	v_lshlrev_b64 v[148:149], 1, v[148:149]
	v_lshl_add_u64 v[152:153], v[150:151], 0, v[148:149]
	v_lshl_add_u64 v[150:151], v[138:139], 2, s[2:3]
	s_mov_b64 s[42:43], -1
	s_andn2_b64 vcc, exec, s[40:41]
	v_mov_b32_e32 v154, 0xbfb8aa3b
	v_mov_b32_e32 v155, 0xbfb8aa3b
	v_mov_b32_e32 v156, 1.0
	v_mov_b32_e32 v157, 1.0
	v_mov_b32_e32 v159, 0
	v_pk_mul_f32 v[128:129], v[128:129], v[224:225] op_sel_hi:[1,0]
	v_pk_mul_f32 v[130:131], v[130:131], v[224:225] op_sel_hi:[1,0]
	v_pk_mul_f32 v[124:125], v[124:125], v[224:225] op_sel_hi:[1,0]
	v_pk_mul_f32 v[126:127], v[126:127], v[224:225] op_sel_hi:[1,0]
	v_pk_mul_f32 v[162:163], v[128:129], v[154:155]
	v_pk_mul_f32 v[164:165], v[130:131], v[154:155]
	v_pk_mul_f32 v[166:167], v[124:125], v[154:155]
	v_pk_mul_f32 v[168:169], v[126:127], v[154:155]
	v_exp_f32_e32 v162, v162
	v_exp_f32_e32 v163, v163
	v_exp_f32_e32 v164, v164
	v_exp_f32_e32 v165, v165
	v_exp_f32_e32 v166, v166
	v_exp_f32_e32 v167, v167
	v_exp_f32_e32 v168, v168
	v_exp_f32_e32 v169, v169
	v_pk_mul_f32 v[120:121], v[120:121], v[224:225] op_sel_hi:[1,0]
	v_pk_mul_f32 v[122:123], v[122:123], v[224:225] op_sel_hi:[1,0]
	v_pk_mul_f32 v[116:117], v[116:117], v[224:225] op_sel_hi:[1,0]
	v_pk_mul_f32 v[118:119], v[118:119], v[224:225] op_sel_hi:[1,0]
	v_pk_add_f32 v[162:163], v[162:163], v[156:157]
	v_pk_add_f32 v[164:165], v[164:165], v[156:157]
	v_pk_add_f32 v[166:167], v[166:167], v[156:157]
	v_pk_add_f32 v[168:169], v[168:169], v[156:157]
	v_rcp_f32_e32 v162, v162
	v_rcp_f32_e32 v163, v163
	v_rcp_f32_e32 v164, v164
	v_rcp_f32_e32 v165, v165
	v_rcp_f32_e32 v166, v166
	v_rcp_f32_e32 v167, v167
	v_rcp_f32_e32 v168, v168
	v_rcp_f32_e32 v169, v169
	v_pk_mul_f32 v[128:129], v[128:129], v[120:121]
	v_pk_mul_f32 v[130:131], v[130:131], v[122:123]
	v_pk_mul_f32 v[124:125], v[124:125], v[116:117]
	v_pk_mul_f32 v[126:127], v[126:127], v[118:119]
	v_pk_mul_f32 v[128:129], v[128:129], v[162:163]
	v_pk_mul_f32 v[130:131], v[130:131], v[164:165]
	v_pk_mul_f32 v[124:125], v[124:125], v[166:167]
	v_pk_mul_f32 v[126:127], v[126:127], v[168:169]
	v_cvt_pk_bf16_f32 v170, v128, v129
	v_cvt_pk_bf16_f32 v171, v130, v131
	v_cvt_pk_bf16_f32 v172, v124, v125
	v_cvt_pk_bf16_f32 v173, v126, v127
	global_store_dwordx4 v[152:153], v[170:173], off
	v_pk_mul_f32 v[112:113], v[112:113], v[226:227] op_sel_hi:[1,0]
	v_pk_mul_f32 v[114:115], v[114:115], v[226:227] op_sel_hi:[1,0]
	v_pk_mul_f32 v[108:109], v[108:109], v[226:227] op_sel_hi:[1,0]
	v_pk_mul_f32 v[110:111], v[110:111], v[226:227] op_sel_hi:[1,0]
	v_pk_mul_f32 v[162:163], v[112:113], v[154:155]
	v_pk_mul_f32 v[164:165], v[114:115], v[154:155]
	v_pk_mul_f32 v[166:167], v[108:109], v[154:155]
	v_pk_mul_f32 v[168:169], v[110:111], v[154:155]
	v_exp_f32_e32 v162, v162
	v_exp_f32_e32 v163, v163
	v_exp_f32_e32 v164, v164
	v_exp_f32_e32 v165, v165
	v_exp_f32_e32 v166, v166
	v_exp_f32_e32 v167, v167
	v_exp_f32_e32 v168, v168
	v_exp_f32_e32 v169, v169
	v_pk_mul_f32 v[104:105], v[104:105], v[226:227] op_sel_hi:[1,0]
	v_pk_mul_f32 v[106:107], v[106:107], v[226:227] op_sel_hi:[1,0]
	v_pk_mul_f32 v[100:101], v[100:101], v[226:227] op_sel_hi:[1,0]
	v_pk_mul_f32 v[102:103], v[102:103], v[226:227] op_sel_hi:[1,0]
	v_pk_add_f32 v[162:163], v[162:163], v[156:157]
	v_pk_add_f32 v[164:165], v[164:165], v[156:157]
	v_pk_add_f32 v[166:167], v[166:167], v[156:157]
	v_pk_add_f32 v[168:169], v[168:169], v[156:157]
	v_rcp_f32_e32 v162, v162
	v_rcp_f32_e32 v163, v163
	v_rcp_f32_e32 v164, v164
	v_rcp_f32_e32 v165, v165
	v_rcp_f32_e32 v166, v166
	v_rcp_f32_e32 v167, v167
	v_rcp_f32_e32 v168, v168
	v_rcp_f32_e32 v169, v169
	v_pk_mul_f32 v[112:113], v[112:113], v[104:105]
	v_pk_mul_f32 v[114:115], v[114:115], v[106:107]
	v_pk_mul_f32 v[108:109], v[108:109], v[100:101]
	v_pk_mul_f32 v[110:111], v[110:111], v[102:103]
	v_pk_mul_f32 v[112:113], v[112:113], v[162:163]
	v_pk_mul_f32 v[114:115], v[114:115], v[164:165]
	v_pk_mul_f32 v[108:109], v[108:109], v[166:167]
	v_pk_mul_f32 v[110:111], v[110:111], v[168:169]
	v_cvt_pk_bf16_f32 v186, v112, v113
	v_cvt_pk_bf16_f32 v187, v114, v115
	v_cvt_pk_bf16_f32 v188, v108, v109
	v_cvt_pk_bf16_f32 v189, v110, v111
	v_mov_b32_e32 v158, 0x16000
	v_lshl_add_u64 v[160:161], v[152:153], 0, v[158:159]
	global_store_dwordx4 v[160:161], v[186:189], off
	v_pk_mul_f32 v[96:97], v[96:97], v[228:229] op_sel_hi:[1,0]
	v_pk_mul_f32 v[98:99], v[98:99], v[228:229] op_sel_hi:[1,0]
	v_pk_mul_f32 v[92:93], v[92:93], v[228:229] op_sel_hi:[1,0]
	v_pk_mul_f32 v[94:95], v[94:95], v[228:229] op_sel_hi:[1,0]
	v_pk_mul_f32 v[162:163], v[96:97], v[154:155]
	v_pk_mul_f32 v[164:165], v[98:99], v[154:155]
	v_pk_mul_f32 v[166:167], v[92:93], v[154:155]
	v_pk_mul_f32 v[168:169], v[94:95], v[154:155]
	v_exp_f32_e32 v162, v162
	v_exp_f32_e32 v163, v163
	v_exp_f32_e32 v164, v164
	v_exp_f32_e32 v165, v165
	v_exp_f32_e32 v166, v166
	v_exp_f32_e32 v167, v167
	v_exp_f32_e32 v168, v168
	v_exp_f32_e32 v169, v169
	v_pk_mul_f32 v[88:89], v[88:89], v[228:229] op_sel_hi:[1,0]
	v_pk_mul_f32 v[90:91], v[90:91], v[228:229] op_sel_hi:[1,0]
	v_pk_mul_f32 v[84:85], v[84:85], v[228:229] op_sel_hi:[1,0]
	v_pk_mul_f32 v[86:87], v[86:87], v[228:229] op_sel_hi:[1,0]
	v_pk_add_f32 v[162:163], v[162:163], v[156:157]
	v_pk_add_f32 v[164:165], v[164:165], v[156:157]
	v_pk_add_f32 v[166:167], v[166:167], v[156:157]
	v_pk_add_f32 v[168:169], v[168:169], v[156:157]
	v_rcp_f32_e32 v162, v162
	v_rcp_f32_e32 v163, v163
	v_rcp_f32_e32 v164, v164
	v_rcp_f32_e32 v165, v165
	v_rcp_f32_e32 v166, v166
	v_rcp_f32_e32 v167, v167
	v_rcp_f32_e32 v168, v168
	v_rcp_f32_e32 v169, v169
	v_pk_mul_f32 v[96:97], v[96:97], v[88:89]
	v_pk_mul_f32 v[98:99], v[98:99], v[90:91]
	v_pk_mul_f32 v[92:93], v[92:93], v[84:85]
	v_pk_mul_f32 v[94:95], v[94:95], v[86:87]
	v_pk_mul_f32 v[96:97], v[96:97], v[162:163]
	v_pk_mul_f32 v[98:99], v[98:99], v[164:165]
	v_pk_mul_f32 v[92:93], v[92:93], v[166:167]
	v_pk_mul_f32 v[94:95], v[94:95], v[168:169]
	v_cvt_pk_bf16_f32 v170, v96, v97
	v_cvt_pk_bf16_f32 v171, v98, v99
	v_cvt_pk_bf16_f32 v172, v92, v93
	v_cvt_pk_bf16_f32 v173, v94, v95
	v_mov_b32_e32 v158, 0x2c000
	v_lshl_add_u64 v[160:161], v[152:153], 0, v[158:159]
	global_store_dwordx4 v[160:161], v[170:173], off
	v_pk_mul_f32 v[80:81], v[80:81], v[230:231] op_sel_hi:[1,0]
	v_pk_mul_f32 v[82:83], v[82:83], v[230:231] op_sel_hi:[1,0]
	v_pk_mul_f32 v[76:77], v[76:77], v[230:231] op_sel_hi:[1,0]
	v_pk_mul_f32 v[78:79], v[78:79], v[230:231] op_sel_hi:[1,0]
	v_pk_mul_f32 v[162:163], v[80:81], v[154:155]
	v_pk_mul_f32 v[164:165], v[82:83], v[154:155]
	v_pk_mul_f32 v[166:167], v[76:77], v[154:155]
	v_pk_mul_f32 v[168:169], v[78:79], v[154:155]
	v_exp_f32_e32 v162, v162
	v_exp_f32_e32 v163, v163
	v_exp_f32_e32 v164, v164
	v_exp_f32_e32 v165, v165
	v_exp_f32_e32 v166, v166
	v_exp_f32_e32 v167, v167
	v_exp_f32_e32 v168, v168
	v_exp_f32_e32 v169, v169
	v_pk_mul_f32 v[72:73], v[72:73], v[230:231] op_sel_hi:[1,0]
	v_pk_mul_f32 v[74:75], v[74:75], v[230:231] op_sel_hi:[1,0]
	v_pk_mul_f32 v[68:69], v[68:69], v[230:231] op_sel_hi:[1,0]
	v_pk_mul_f32 v[70:71], v[70:71], v[230:231] op_sel_hi:[1,0]
	v_pk_add_f32 v[162:163], v[162:163], v[156:157]
	v_pk_add_f32 v[164:165], v[164:165], v[156:157]
	v_pk_add_f32 v[166:167], v[166:167], v[156:157]
	v_pk_add_f32 v[168:169], v[168:169], v[156:157]
	v_rcp_f32_e32 v162, v162
	v_rcp_f32_e32 v163, v163
	v_rcp_f32_e32 v164, v164
	v_rcp_f32_e32 v165, v165
	v_rcp_f32_e32 v166, v166
	v_rcp_f32_e32 v167, v167
	v_rcp_f32_e32 v168, v168
	v_rcp_f32_e32 v169, v169
	v_pk_mul_f32 v[80:81], v[80:81], v[72:73]
	v_pk_mul_f32 v[82:83], v[82:83], v[74:75]
	v_pk_mul_f32 v[76:77], v[76:77], v[68:69]
	v_pk_mul_f32 v[78:79], v[78:79], v[70:71]
	v_pk_mul_f32 v[80:81], v[80:81], v[162:163]
	v_pk_mul_f32 v[82:83], v[82:83], v[164:165]
	v_pk_mul_f32 v[76:77], v[76:77], v[166:167]
	v_pk_mul_f32 v[78:79], v[78:79], v[168:169]
	v_cvt_pk_bf16_f32 v186, v80, v81
	v_cvt_pk_bf16_f32 v187, v82, v83
	v_cvt_pk_bf16_f32 v188, v76, v77
	v_cvt_pk_bf16_f32 v189, v78, v79
	v_mov_b32_e32 v158, 0x42000
	v_lshl_add_u64 v[160:161], v[152:153], 0, v[158:159]
	global_store_dwordx4 v[160:161], v[186:189], off
	v_pk_mul_f32 v[64:65], v[64:65], v[232:233] op_sel_hi:[1,0]
	v_pk_mul_f32 v[66:67], v[66:67], v[232:233] op_sel_hi:[1,0]
	v_pk_mul_f32 v[60:61], v[60:61], v[232:233] op_sel_hi:[1,0]
	v_pk_mul_f32 v[62:63], v[62:63], v[232:233] op_sel_hi:[1,0]
	v_pk_mul_f32 v[162:163], v[64:65], v[154:155]
	v_pk_mul_f32 v[164:165], v[66:67], v[154:155]
	v_pk_mul_f32 v[166:167], v[60:61], v[154:155]
	v_pk_mul_f32 v[168:169], v[62:63], v[154:155]
	v_exp_f32_e32 v162, v162
	v_exp_f32_e32 v163, v163
	v_exp_f32_e32 v164, v164
	v_exp_f32_e32 v165, v165
	v_exp_f32_e32 v166, v166
	v_exp_f32_e32 v167, v167
	v_exp_f32_e32 v168, v168
	v_exp_f32_e32 v169, v169
	v_pk_mul_f32 v[56:57], v[56:57], v[232:233] op_sel_hi:[1,0]
	v_pk_mul_f32 v[58:59], v[58:59], v[232:233] op_sel_hi:[1,0]
	v_pk_mul_f32 v[52:53], v[52:53], v[232:233] op_sel_hi:[1,0]
	v_pk_mul_f32 v[54:55], v[54:55], v[232:233] op_sel_hi:[1,0]
	v_pk_add_f32 v[162:163], v[162:163], v[156:157]
	v_pk_add_f32 v[164:165], v[164:165], v[156:157]
	v_pk_add_f32 v[166:167], v[166:167], v[156:157]
	v_pk_add_f32 v[168:169], v[168:169], v[156:157]
	v_rcp_f32_e32 v162, v162
	v_rcp_f32_e32 v163, v163
	v_rcp_f32_e32 v164, v164
	v_rcp_f32_e32 v165, v165
	v_rcp_f32_e32 v166, v166
	v_rcp_f32_e32 v167, v167
	v_rcp_f32_e32 v168, v168
	v_rcp_f32_e32 v169, v169
	v_pk_mul_f32 v[64:65], v[64:65], v[56:57]
	v_pk_mul_f32 v[66:67], v[66:67], v[58:59]
	v_pk_mul_f32 v[60:61], v[60:61], v[52:53]
	v_pk_mul_f32 v[62:63], v[62:63], v[54:55]
	v_pk_mul_f32 v[64:65], v[64:65], v[162:163]
	v_pk_mul_f32 v[66:67], v[66:67], v[164:165]
	v_pk_mul_f32 v[60:61], v[60:61], v[166:167]
	v_pk_mul_f32 v[62:63], v[62:63], v[168:169]
	v_cvt_pk_bf16_f32 v170, v64, v65
	v_cvt_pk_bf16_f32 v171, v66, v67
	v_cvt_pk_bf16_f32 v172, v60, v61
	v_cvt_pk_bf16_f32 v173, v62, v63
	v_mov_b32_e32 v158, 0xb0000
	v_lshl_add_u64 v[160:161], v[152:153], 0, v[158:159]
	global_store_dwordx4 v[160:161], v[170:173], off
	v_pk_mul_f32 v[48:49], v[48:49], v[234:235] op_sel_hi:[1,0]
	v_pk_mul_f32 v[50:51], v[50:51], v[234:235] op_sel_hi:[1,0]
	v_pk_mul_f32 v[44:45], v[44:45], v[234:235] op_sel_hi:[1,0]
	v_pk_mul_f32 v[46:47], v[46:47], v[234:235] op_sel_hi:[1,0]
	v_pk_mul_f32 v[162:163], v[48:49], v[154:155]
	v_pk_mul_f32 v[164:165], v[50:51], v[154:155]
	v_pk_mul_f32 v[166:167], v[44:45], v[154:155]
	v_pk_mul_f32 v[168:169], v[46:47], v[154:155]
	v_exp_f32_e32 v162, v162
	v_exp_f32_e32 v163, v163
	v_exp_f32_e32 v164, v164
	v_exp_f32_e32 v165, v165
	v_exp_f32_e32 v166, v166
	v_exp_f32_e32 v167, v167
	v_exp_f32_e32 v168, v168
	v_exp_f32_e32 v169, v169
	v_pk_mul_f32 v[40:41], v[40:41], v[234:235] op_sel_hi:[1,0]
	v_pk_mul_f32 v[42:43], v[42:43], v[234:235] op_sel_hi:[1,0]
	v_pk_mul_f32 v[36:37], v[36:37], v[234:235] op_sel_hi:[1,0]
	v_pk_mul_f32 v[38:39], v[38:39], v[234:235] op_sel_hi:[1,0]
	v_pk_add_f32 v[162:163], v[162:163], v[156:157]
	v_pk_add_f32 v[164:165], v[164:165], v[156:157]
	v_pk_add_f32 v[166:167], v[166:167], v[156:157]
	v_pk_add_f32 v[168:169], v[168:169], v[156:157]
	v_rcp_f32_e32 v162, v162
	v_rcp_f32_e32 v163, v163
	v_rcp_f32_e32 v164, v164
	v_rcp_f32_e32 v165, v165
	v_rcp_f32_e32 v166, v166
	v_rcp_f32_e32 v167, v167
	v_rcp_f32_e32 v168, v168
	v_rcp_f32_e32 v169, v169
	v_pk_mul_f32 v[48:49], v[48:49], v[40:41]
	v_pk_mul_f32 v[50:51], v[50:51], v[42:43]
	v_pk_mul_f32 v[44:45], v[44:45], v[36:37]
	v_pk_mul_f32 v[46:47], v[46:47], v[38:39]
	v_pk_mul_f32 v[48:49], v[48:49], v[162:163]
	v_pk_mul_f32 v[50:51], v[50:51], v[164:165]
	v_pk_mul_f32 v[44:45], v[44:45], v[166:167]
	v_pk_mul_f32 v[46:47], v[46:47], v[168:169]
	v_cvt_pk_bf16_f32 v186, v48, v49
	v_cvt_pk_bf16_f32 v187, v50, v51
	v_cvt_pk_bf16_f32 v188, v44, v45
	v_cvt_pk_bf16_f32 v189, v46, v47
	v_mov_b32_e32 v158, 0xc6000
	v_lshl_add_u64 v[160:161], v[152:153], 0, v[158:159]
	global_store_dwordx4 v[160:161], v[186:189], off
	v_pk_mul_f32 v[32:33], v[32:33], v[236:237] op_sel_hi:[1,0]
	v_pk_mul_f32 v[34:35], v[34:35], v[236:237] op_sel_hi:[1,0]
	v_pk_mul_f32 v[28:29], v[28:29], v[236:237] op_sel_hi:[1,0]
	v_pk_mul_f32 v[30:31], v[30:31], v[236:237] op_sel_hi:[1,0]
	v_pk_mul_f32 v[162:163], v[32:33], v[154:155]
	v_pk_mul_f32 v[164:165], v[34:35], v[154:155]
	v_pk_mul_f32 v[166:167], v[28:29], v[154:155]
	v_pk_mul_f32 v[168:169], v[30:31], v[154:155]
	v_exp_f32_e32 v162, v162
	v_exp_f32_e32 v163, v163
	v_exp_f32_e32 v164, v164
	v_exp_f32_e32 v165, v165
	v_exp_f32_e32 v166, v166
	v_exp_f32_e32 v167, v167
	v_exp_f32_e32 v168, v168
	v_exp_f32_e32 v169, v169
	v_pk_mul_f32 v[24:25], v[24:25], v[236:237] op_sel_hi:[1,0]
	v_pk_mul_f32 v[26:27], v[26:27], v[236:237] op_sel_hi:[1,0]
	v_pk_mul_f32 v[20:21], v[20:21], v[236:237] op_sel_hi:[1,0]
	v_pk_mul_f32 v[22:23], v[22:23], v[236:237] op_sel_hi:[1,0]
	v_pk_add_f32 v[162:163], v[162:163], v[156:157]
	v_pk_add_f32 v[164:165], v[164:165], v[156:157]
	v_pk_add_f32 v[166:167], v[166:167], v[156:157]
	v_pk_add_f32 v[168:169], v[168:169], v[156:157]
	v_rcp_f32_e32 v162, v162
	v_rcp_f32_e32 v163, v163
	v_rcp_f32_e32 v164, v164
	v_rcp_f32_e32 v165, v165
	v_rcp_f32_e32 v166, v166
	v_rcp_f32_e32 v167, v167
	v_rcp_f32_e32 v168, v168
	v_rcp_f32_e32 v169, v169
	v_pk_mul_f32 v[32:33], v[32:33], v[24:25]
	v_pk_mul_f32 v[34:35], v[34:35], v[26:27]
	v_pk_mul_f32 v[28:29], v[28:29], v[20:21]
	v_pk_mul_f32 v[30:31], v[30:31], v[22:23]
	v_pk_mul_f32 v[32:33], v[32:33], v[162:163]
	v_pk_mul_f32 v[34:35], v[34:35], v[164:165]
	v_pk_mul_f32 v[28:29], v[28:29], v[166:167]
	v_pk_mul_f32 v[30:31], v[30:31], v[168:169]
	v_cvt_pk_bf16_f32 v170, v32, v33
	v_cvt_pk_bf16_f32 v171, v34, v35
	v_cvt_pk_bf16_f32 v172, v28, v29
	v_cvt_pk_bf16_f32 v173, v30, v31
	v_mov_b32_e32 v158, 0xdc000
	v_lshl_add_u64 v[160:161], v[152:153], 0, v[158:159]
	global_store_dwordx4 v[160:161], v[170:173], off
	v_pk_mul_f32 v[16:17], v[16:17], v[238:239] op_sel_hi:[1,0]
	v_pk_mul_f32 v[18:19], v[18:19], v[238:239] op_sel_hi:[1,0]
	v_pk_mul_f32 v[12:13], v[12:13], v[238:239] op_sel_hi:[1,0]
	v_pk_mul_f32 v[14:15], v[14:15], v[238:239] op_sel_hi:[1,0]
	v_pk_mul_f32 v[162:163], v[16:17], v[154:155]
	v_pk_mul_f32 v[164:165], v[18:19], v[154:155]
	v_pk_mul_f32 v[166:167], v[12:13], v[154:155]
	v_pk_mul_f32 v[168:169], v[14:15], v[154:155]
	v_exp_f32_e32 v162, v162
	v_exp_f32_e32 v163, v163
	v_exp_f32_e32 v164, v164
	v_exp_f32_e32 v165, v165
	v_exp_f32_e32 v166, v166
	v_exp_f32_e32 v167, v167
	v_exp_f32_e32 v168, v168
	v_exp_f32_e32 v169, v169
	v_pk_mul_f32 v[8:9], v[8:9], v[238:239] op_sel_hi:[1,0]
	v_pk_mul_f32 v[10:11], v[10:11], v[238:239] op_sel_hi:[1,0]
	v_pk_mul_f32 v[4:5], v[4:5], v[238:239] op_sel_hi:[1,0]
	v_pk_mul_f32 v[6:7], v[6:7], v[238:239] op_sel_hi:[1,0]
	v_pk_add_f32 v[162:163], v[162:163], v[156:157]
	v_pk_add_f32 v[164:165], v[164:165], v[156:157]
	v_pk_add_f32 v[166:167], v[166:167], v[156:157]
	v_pk_add_f32 v[168:169], v[168:169], v[156:157]
	v_rcp_f32_e32 v162, v162
	v_rcp_f32_e32 v163, v163
	v_rcp_f32_e32 v164, v164
	v_rcp_f32_e32 v165, v165
	v_rcp_f32_e32 v166, v166
	v_rcp_f32_e32 v167, v167
	v_rcp_f32_e32 v168, v168
	v_rcp_f32_e32 v169, v169
	v_pk_mul_f32 v[16:17], v[16:17], v[8:9]
	v_pk_mul_f32 v[18:19], v[18:19], v[10:11]
	v_pk_mul_f32 v[12:13], v[12:13], v[4:5]
	v_pk_mul_f32 v[14:15], v[14:15], v[6:7]
	v_pk_mul_f32 v[16:17], v[16:17], v[162:163]
	v_pk_mul_f32 v[18:19], v[18:19], v[164:165]
	v_pk_mul_f32 v[12:13], v[12:13], v[166:167]
	v_pk_mul_f32 v[14:15], v[14:15], v[168:169]
	v_cvt_pk_bf16_f32 v186, v16, v17
	v_cvt_pk_bf16_f32 v187, v18, v19
	v_cvt_pk_bf16_f32 v188, v12, v13
	v_cvt_pk_bf16_f32 v189, v14, v15
	v_mov_b32_e32 v158, 0xf2000
	v_lshl_add_u64 v[160:161], v[152:153], 0, v[158:159]
	global_store_dwordx4 v[160:161], v[186:189], off
	s_cbranch_vccnz .LBB0_496
	s_and_b64 vcc, exec, s[38:39]
	s_cbranch_vccnz .LBB0_495
	s_barrier
	s_branch .LBB0_495
